# adds: non-temporal policy on last-use residual loads of both residual epilogues, on the final output row stores and on the state-scan chunk loads
# baseline (speedup 1.0000x reference)
; __device__ __forceinline__ unsigned cvt_pk_bf16(float lo, float hi) { unsigned r; asm volatile("v_cvt_pk_bf16_f32 %0, %1, %2" : "=v"(r) : "v"(lo), "v"(hi)); return r; }
; __device__ __forceinline__ void mlstm_state_scan(const Frame& F) {
;     ...
;     if (F.tid < 128) { const int h = F.tid >> 5, c = F.tid & 31; const float* MR = MRb + h * SP; sdec[F.tid] = expf((c == 0 ? 0.f : MR[c * LC - 1]) - MR[c * LC + LC - 1]); }
;     __syncthreads();
;     const int gt = F.bid * 512 + F.tid, GT = F.G * 512;
;     typedef float f32x2 __attribute__((ext_vector_type(2)));
;     for (int e2 = gt; e2 < 131072; e2 += GT) { const int h = e2 >> 15;
;         f32x2 C = (f32x2){0.f, 0.f};
; #pragma unroll 1
;         for (int c0 = 0; c0 < NCH; c0 += 8) { f32x2 u[8];
; #pragma unroll
;             for (int k = 0; k < 8; ++k) u[k] = *(const f32x2*)(U + (size_t)(c0 + k) * 262144 + (size_t)e2 * 2);
; #pragma unroll
;             for (int k = 0; k < 8; ++k) { *(unsigned*)(CST + (size_t)(c0 + k) * 262144 + (size_t)e2 * 2) = cvt_pk_bf16(C[0], C[1]); C = C * sdec[h * 32 + c0 + k] + u[k]; } }
;         *(f32x2*)(F.out + O_CP + (size_t)e2 * 2) = C; }
.LBB0_672:
	s_cmp_lt_i32 s86, 6
	s_cselect_b64 s[2:3], -1, 0
	s_waitcnt lgkmcnt(0)
	s_and_b64 s[18:19], s[2:3], s[0:1]
	s_andn2_b64 vcc, exec, s[18:19]
	s_cbranch_vccnz .LBB0_686
	v_lshl_add_u32 v104, s33, 9, v144
	v_lshlrev_b32_e32 v104, 3, v104
	v_mov_b32_e32 v105, 0
	v_lshl_add_u64 v[12:13], s[84:85], 0, v[104:105]
	v_add_co_u32_e32 v14, vcc, 0x17dc0000, v12
	s_nop 1
	v_addc_co_u32_e32 v15, vcc, 0, v13, vcc
	global_load_dwordx2 v[40:41], v[14:15], off offset:256 nt
	v_add_co_u32_e32 v14, vcc, 0x17ec0000, v12
	s_nop 1
	v_addc_co_u32_e32 v15, vcc, 0, v13, vcc
	global_load_dwordx2 v[42:43], v[14:15], off offset:256 nt
	v_add_co_u32_e32 v14, vcc, 0x17fc0000, v12
	s_nop 1
	v_addc_co_u32_e32 v15, vcc, 0, v13, vcc
	global_load_dwordx2 v[44:45], v[14:15], off offset:256 nt
	v_add_co_u32_e32 v14, vcc, 0x180c0000, v12
	s_nop 1
	v_addc_co_u32_e32 v15, vcc, 0, v13, vcc
	global_load_dwordx2 v[46:47], v[14:15], off offset:256 nt
	v_add_co_u32_e32 v14, vcc, 0x181c0000, v12
	s_nop 1
	v_addc_co_u32_e32 v15, vcc, 0, v13, vcc
	global_load_dwordx2 v[48:49], v[14:15], off offset:256 nt
	v_add_co_u32_e32 v14, vcc, 0x182c0000, v12
	s_nop 1
	v_addc_co_u32_e32 v15, vcc, 0, v13, vcc
	global_load_dwordx2 v[50:51], v[14:15], off offset:256 nt
	v_add_co_u32_e32 v14, vcc, 0x183c0000, v12
	s_nop 1
	v_addc_co_u32_e32 v15, vcc, 0, v13, vcc
	global_load_dwordx2 v[52:53], v[14:15], off offset:256 nt
	v_add_co_u32_e32 v14, vcc, 0x184c0000, v12
	s_nop 1
	v_addc_co_u32_e32 v15, vcc, 0, v13, vcc
	global_load_dwordx2 v[54:55], v[14:15], off offset:256 nt
	v_add_co_u32_e32 v14, vcc, 0x185c0000, v12
	s_nop 1
	v_addc_co_u32_e32 v15, vcc, 0, v13, vcc
	global_load_dwordx2 v[56:57], v[14:15], off offset:256 nt
	v_add_co_u32_e32 v14, vcc, 0x186c0000, v12
	s_nop 1
	v_addc_co_u32_e32 v15, vcc, 0, v13, vcc
	global_load_dwordx2 v[58:59], v[14:15], off offset:256 nt
	v_add_co_u32_e32 v14, vcc, 0x187c0000, v12
	s_nop 1
	v_addc_co_u32_e32 v15, vcc, 0, v13, vcc
	global_load_dwordx2 v[60:61], v[14:15], off offset:256 nt
	v_add_co_u32_e32 v14, vcc, 0x188c0000, v12
	s_nop 1
	v_addc_co_u32_e32 v15, vcc, 0, v13, vcc
	global_load_dwordx2 v[62:63], v[14:15], off offset:256 nt
	v_add_co_u32_e32 v14, vcc, 0x189c0000, v12
	s_nop 1
	v_addc_co_u32_e32 v15, vcc, 0, v13, vcc
	global_load_dwordx2 v[64:65], v[14:15], off offset:256 nt
	v_add_co_u32_e32 v14, vcc, 0x18ac0000, v12
	s_nop 1
	v_addc_co_u32_e32 v15, vcc, 0, v13, vcc
	global_load_dwordx2 v[66:67], v[14:15], off offset:256 nt
	v_add_co_u32_e32 v14, vcc, 0x18bc0000, v12
	s_nop 1
	v_addc_co_u32_e32 v15, vcc, 0, v13, vcc
	global_load_dwordx2 v[68:69], v[14:15], off offset:256 nt
	v_add_co_u32_e32 v14, vcc, 0x18cc0000, v12
	s_nop 1
	v_addc_co_u32_e32 v15, vcc, 0, v13, vcc
	global_load_dwordx2 v[70:71], v[14:15], off offset:256 nt
	v_add_co_u32_e32 v14, vcc, 0x18dc0000, v12
	s_nop 1
	v_addc_co_u32_e32 v15, vcc, 0, v13, vcc
	global_load_dwordx2 v[72:73], v[14:15], off offset:256 nt
	v_add_co_u32_e32 v14, vcc, 0x18ec0000, v12
	s_nop 1
	v_addc_co_u32_e32 v15, vcc, 0, v13, vcc
	global_load_dwordx2 v[74:75], v[14:15], off offset:256 nt
	v_add_co_u32_e32 v14, vcc, 0x18fc0000, v12
	s_nop 1
	v_addc_co_u32_e32 v15, vcc, 0, v13, vcc
	global_load_dwordx2 v[76:77], v[14:15], off offset:256 nt
	v_add_co_u32_e32 v14, vcc, 0x190c0000, v12
	s_nop 1
	v_addc_co_u32_e32 v15, vcc, 0, v13, vcc
	global_load_dwordx2 v[78:79], v[14:15], off offset:256 nt
	v_add_co_u32_e32 v14, vcc, 0x191c0000, v12
	s_nop 1
	v_addc_co_u32_e32 v15, vcc, 0, v13, vcc
	global_load_dwordx2 v[80:81], v[14:15], off offset:256 nt
	v_add_co_u32_e32 v14, vcc, 0x192c0000, v12
	s_nop 1
	v_addc_co_u32_e32 v15, vcc, 0, v13, vcc
	global_load_dwordx2 v[82:83], v[14:15], off offset:256 nt
	v_add_co_u32_e32 v14, vcc, 0x193c0000, v12
	s_nop 1
	v_addc_co_u32_e32 v15, vcc, 0, v13, vcc
	global_load_dwordx2 v[84:85], v[14:15], off offset:256 nt
	v_add_co_u32_e32 v14, vcc, 0x194c0000, v12
	s_nop 1
	v_addc_co_u32_e32 v15, vcc, 0, v13, vcc
	global_load_dwordx2 v[86:87], v[14:15], off offset:256 nt
	v_add_co_u32_e32 v14, vcc, 0x195c0000, v12
	s_nop 1
	v_addc_co_u32_e32 v15, vcc, 0, v13, vcc
	global_load_dwordx2 v[88:89], v[14:15], off offset:256 nt
	v_add_co_u32_e32 v14, vcc, 0x196c0000, v12
	s_nop 1
	v_addc_co_u32_e32 v15, vcc, 0, v13, vcc
	global_load_dwordx2 v[90:91], v[14:15], off offset:256 nt
	v_add_co_u32_e32 v14, vcc, 0x197c0000, v12
	s_nop 1
	v_addc_co_u32_e32 v15, vcc, 0, v13, vcc
	global_load_dwordx2 v[92:93], v[14:15], off offset:256 nt
	v_add_co_u32_e32 v14, vcc, 0x198c0000, v12
	s_nop 1
	v_addc_co_u32_e32 v15, vcc, 0, v13, vcc
	global_load_dwordx2 v[94:95], v[14:15], off offset:256 nt
	v_add_co_u32_e32 v14, vcc, 0x199c0000, v12
	s_nop 1
	v_addc_co_u32_e32 v15, vcc, 0, v13, vcc
	global_load_dwordx2 v[96:97], v[14:15], off offset:256 nt
	v_add_co_u32_e32 v14, vcc, 0x19ac0000, v12
	s_nop 1
	v_addc_co_u32_e32 v15, vcc, 0, v13, vcc
	global_load_dwordx2 v[98:99], v[14:15], off offset:256 nt
	v_add_co_u32_e32 v14, vcc, 0x19bc0000, v12
	s_nop 1
	v_addc_co_u32_e32 v15, vcc, 0, v13, vcc
	global_load_dwordx2 v[100:101], v[14:15], off offset:256 nt
	v_add_co_u32_e32 v14, vcc, 0x19cc0000, v12
	s_nop 1
	v_addc_co_u32_e32 v15, vcc, 0, v13, vcc
	global_load_dwordx2 v[102:103], v[14:15], off offset:256 nt
	s_movk_i32 s0, 0x80
	v_cmp_gt_u32_e32 vcc, s0, v144
	s_and_saveexec_b64 s[0:1], vcc
	s_cbranch_execz .LBB0_677
	s_waitcnt vmcnt(0)
	v_lshlrev_b32_e32 v0, 10, v144
	v_and_b32_e32 v0, 0x18000, v0
	v_mov_b32_e32 v1, 0
	v_and_b32_e32 v6, 31, v144
	v_lshl_add_u64 v[2:3], s[84:85], 0, v[0:1]
	s_mov_b64 s[2:3], 0x17da0100
	v_mov_b64_e32 v[4:5], 0
	v_lshl_add_u64 v[2:3], v[2:3], 0, s[2:3]
	v_cmp_ne_u32_e32 vcc, 0, v6
	v_mov_b32_e32 v5, 0
	s_and_saveexec_b64 s[2:3], vcc
	s_cbranch_execz .LBB0_676
	v_mov_b32_e32 v5, 0
	v_lshlrev_b32_e32 v4, 10, v6
	v_lshl_add_u64 v[4:5], v[2:3], 0, v[4:5]
	global_load_dword v5, v[4:5], off offset:-4
	v_lshlrev_b32_e32 v4, 8, v6

;     __device__ __forceinline__ void operator()(const f32x4 (&acc)[2][2][4][2], const Unit& u, int wr, int wc, int fr, int fq) const {
;     ...
;         f32x4 gv[2][2];
; #pragma unroll
;         for (int bj = 0; bj < 2; ++bj)
; #pragma unroll
;             for (int n = 0; n < 2; ++n) gv[bj][n] = *(const f32x4*)(gate + (size_t)128 * NMOD + col0 + bj * HALF + n * 16);
;         int roff = row0 * D + col0; asm volatile("" : "+v"(roff));
; #pragma unroll
;         for (int am = 0; am < 4; ++am) { f32x4 rv[2][2][2];
; #pragma unroll
;             for (int m2 = 0; m2 < 2; ++m2)
; #pragma unroll
;                 for (int bj = 0; bj < 2; ++bj)
; #pragma unroll
;                     for (int n = 0; n < 2; ++n) rv[m2][bj][n] = *(const f32x4*)(res0 + (roff + ((am >> 1) * HALF + ((am & 1) * 2 + m2) * 16) * D + bj * HALF + n * 16));
; #pragma unroll
;             for (int m2 = 0; m2 < 2; ++m2)
; #pragma unroll
;                 for (int bj = 0; bj < 2; ++bj)
; #pragma unroll
;                     for (int n = 0; n < 2; ++n) *(f32x4*)(out + (roff + ((am >> 1) * HALF + ((am & 1) * 2 + m2) * 16) * D + bj * HALF + n * 16)) = rv[m2][bj][n] + gv[bj][n] * acc[am >> 1][bj][(am & 1) * 2 + m2][n]; }
.LBB0_886:
	v_ashrrev_i32_e32 v163, 31, v162
	v_lshl_add_u64 v[128:129], v[162:163], 2, s[12:13]
	v_lshl_add_u32 v164, v168, 11, v162
	global_load_dwordx4 v[140:143], v[128:129], off
	global_load_dwordx4 v[136:139], v[128:129], off offset:64
	global_load_dwordx4 v[132:135], v[128:129], off offset:512
	s_nop 0
	global_load_dwordx4 v[128:131], v[128:129], off offset:576
	v_readlane_b32 s64, v245, 37
	v_readlane_b32 s65, v245, 38
	v_readlane_b32 s66, v245, 39
	v_readlane_b32 s67, v245, 40
	v_readlane_b32 s68, v245, 41
	v_readlane_b32 s69, v245, 42
	v_readlane_b32 s70, v245, 43
	v_readlane_b32 s71, v245, 44
	v_readlane_b32 s72, v245, 45
	v_readlane_b32 s73, v245, 46
	v_readlane_b32 s74, v245, 47
	v_readlane_b32 s75, v245, 48
	v_readlane_b32 s76, v245, 49
	v_readlane_b32 s77, v245, 50
	v_readlane_b32 s78, v245, 51
	v_readlane_b32 s79, v245, 52
	v_ashrrev_i32_e32 v165, 31, v164
	v_lshlrev_b64 v[222:223], 2, v[164:165]
	s_nop 1
	v_lshl_add_u64 v[220:221], s[64:65], 0, v[222:223]
	v_lshl_add_u64 v[222:223], s[6:7], 0, v[222:223]
	global_load_dwordx4 v[172:175], v[220:221], off nt
	global_load_dwordx4 v[176:179], v[220:221], off offset:64 nt
	global_load_dwordx4 v[180:183], v[220:221], off offset:512 nt
	global_load_dwordx4 v[184:187], v[220:221], off offset:576 nt
	v_add_co_u32_e32 v224, vcc, 0x20000, v220
	s_nop 1
	v_addc_co_u32_e32 v225, vcc, 0, v221, vcc
	global_load_dwordx4 v[188:191], v[224:225], off nt
	global_load_dwordx4 v[192:195], v[224:225], off offset:64 nt
	global_load_dwordx4 v[196:199], v[224:225], off offset:512 nt
	global_load_dwordx4 v[200:203], v[224:225], off offset:576 nt
	v_add_co_u32_e32 v224, vcc, 0x40000, v220
	s_nop 1
	v_addc_co_u32_e32 v225, vcc, 0, v221, vcc
	global_load_dwordx4 v[204:207], v[224:225], off nt
	global_load_dwordx4 v[208:211], v[224:225], off offset:64 nt
	global_load_dwordx4 v[212:215], v[224:225], off offset:512 nt
	global_load_dwordx4 v[216:219], v[224:225], off offset:576 nt
	s_waitcnt vmcnt(8)
	v_pk_fma_f32 v[174:175], v[126:127], v[142:143], v[174:175]
	v_pk_fma_f32 v[172:173], v[124:125], v[140:141], v[172:173]
	global_store_dwordx4 v[222:223], v[172:175], off
	v_pk_fma_f32 v[178:179], v[122:123], v[138:139], v[178:179]
	v_pk_fma_f32 v[176:177], v[120:121], v[136:137], v[176:177]
	global_store_dwordx4 v[222:223], v[176:179], off offset:64
	v_pk_fma_f32 v[182:183], v[110:111], v[134:135], v[182:183]
	v_pk_fma_f32 v[180:181], v[108:109], v[132:133], v[180:181]
	global_store_dwordx4 v[222:223], v[180:183], off offset:512
	v_pk_fma_f32 v[186:187], v[106:107], v[130:131], v[186:187]
	v_pk_fma_f32 v[184:185], v[104:105], v[128:129], v[184:185]
	global_store_dwordx4 v[222:223], v[184:187], off offset:576
	v_add_co_u32_e32 v224, vcc, 0x60000, v220
	s_nop 1
	v_addc_co_u32_e32 v225, vcc, 0, v221, vcc
	global_load_dwordx4 v[172:175], v[224:225], off nt
	global_load_dwordx4 v[176:179], v[224:225], off offset:64 nt
	global_load_dwordx4 v[180:183], v[224:225], off offset:512 nt
	global_load_dwordx4 v[184:187], v[224:225], off offset:576 nt
	s_waitcnt vmcnt(12)
	v_add_co_u32_e32 v226, vcc, 0x20000, v222
	s_nop 1
	v_addc_co_u32_e32 v227, vcc, 0, v223, vcc
	v_pk_fma_f32 v[190:191], v[118:119], v[142:143], v[190:191]
	v_pk_fma_f32 v[188:189], v[116:117], v[140:141], v[188:189]
	global_store_dwordx4 v[226:227], v[188:191], off
	v_pk_fma_f32 v[194:195], v[114:115], v[138:139], v[194:195]
	v_pk_fma_f32 v[192:193], v[112:113], v[136:137], v[192:193]
	global_store_dwordx4 v[226:227], v[192:195], off offset:64
	v_pk_fma_f32 v[198:199], v[102:103], v[134:135], v[198:199]
	v_pk_fma_f32 v[196:197], v[100:101], v[132:133], v[196:197]
	global_store_dwordx4 v[226:227], v[196:199], off offset:512
	v_pk_fma_f32 v[202:203], v[98:99], v[130:131], v[202:203]
	v_pk_fma_f32 v[200:201], v[96:97], v[128:129], v[200:201]
	global_store_dwordx4 v[226:227], v[200:203], off offset:576
	v_add_co_u32_e32 v224, vcc, 0x100000, v220
	s_nop 1
	v_addc_co_u32_e32 v225, vcc, 0, v221, vcc
	global_load_dwordx4 v[188:191], v[224:225], off nt
	global_load_dwordx4 v[192:195], v[224:225], off offset:64 nt
	global_load_dwordx4 v[196:199], v[224:225], off offset:512 nt
	global_load_dwordx4 v[200:203], v[224:225], off offset:576 nt
	s_waitcnt vmcnt(16)
	v_add_co_u32_e32 v226, vcc, 0x40000, v222
	s_nop 1
	v_addc_co_u32_e32 v227, vcc, 0, v223, vcc
	v_pk_fma_f32 v[206:207], v[94:95], v[142:143], v[206:207]
	v_pk_fma_f32 v[204:205], v[92:93], v[140:141], v[204:205]
	global_store_dwordx4 v[226:227], v[204:207], off
	v_pk_fma_f32 v[210:211], v[90:91], v[138:139], v[210:211]
	v_pk_fma_f32 v[208:209], v[88:89], v[136:137], v[208:209]
	global_store_dwordx4 v[226:227], v[208:211], off offset:64
	v_pk_fma_f32 v[214:215], v[78:79], v[134:135], v[214:215]
	v_pk_fma_f32 v[212:213], v[76:77], v[132:133], v[212:213]
	global_store_dwordx4 v[226:227], v[212:215], off offset:512
	v_pk_fma_f32 v[218:219], v[74:75], v[130:131], v[218:219]
	v_pk_fma_f32 v[216:217], v[72:73], v[128:129], v[216:217]
	global_store_dwordx4 v[226:227], v[216:219], off offset:576
	v_add_co_u32_e32 v224, vcc, 0x120000, v220
	s_nop 1
	v_addc_co_u32_e32 v225, vcc, 0, v221, vcc
	global_load_dwordx4 v[204:207], v[224:225], off nt
	global_load_dwordx4 v[208:211], v[224:225], off offset:64 nt
	global_load_dwordx4 v[212:215], v[224:225], off offset:512 nt
	global_load_dwordx4 v[216:219], v[224:225], off offset:576 nt
	s_waitcnt vmcnt(16)
;     __device__ __forceinline__ void operator()(const f32x4 (&acc)[2][2][4][2], const Unit& u, int wr, int wc, int fr, int fq) const {
;     ...
;         for (int am = 0; am < 4; ++am) { f32x4 rv[2][2][2];
; #pragma unroll
;             for (int m2 = 0; m2 < 2; ++m2)
; #pragma unroll
;                 for (int bj = 0; bj < 2; ++bj)
; #pragma unroll
;                     for (int n = 0; n < 2; ++n) rv[m2][bj][n] = *(const f32x4*)(res0 + (roff + ((am >> 1) * HALF + ((am & 1) * 2 + m2) * 16) * D + bj * HALF + n * 16));
; #pragma unroll
;             for (int m2 = 0; m2 < 2; ++m2)
; #pragma unroll
;                 for (int bj = 0; bj < 2; ++bj)
; #pragma unroll
;                     for (int n = 0; n < 2; ++n) *(f32x4*)(out + (roff + ((am >> 1) * HALF + ((am & 1) * 2 + m2) * 16) * D + bj * HALF + n * 16)) = rv[m2][bj][n] + gv[bj][n] * acc[am >> 1][bj][(am & 1) * 2 + m2][n]; }
	v_add_co_u32_e32 v226, vcc, 0x60000, v222
	s_nop 1
	v_addc_co_u32_e32 v227, vcc, 0, v223, vcc
	v_pk_fma_f32 v[174:175], v[86:87], v[142:143], v[174:175]
	v_pk_fma_f32 v[172:173], v[84:85], v[140:141], v[172:173]
	global_store_dwordx4 v[226:227], v[172:175], off
	v_pk_fma_f32 v[178:179], v[82:83], v[138:139], v[178:179]
	v_pk_fma_f32 v[176:177], v[80:81], v[136:137], v[176:177]
	global_store_dwordx4 v[226:227], v[176:179], off offset:64
	v_pk_fma_f32 v[182:183], v[70:71], v[134:135], v[182:183]
	v_pk_fma_f32 v[180:181], v[68:69], v[132:133], v[180:181]
	global_store_dwordx4 v[226:227], v[180:183], off offset:512
	v_pk_fma_f32 v[186:187], v[66:67], v[130:131], v[186:187]
	v_pk_fma_f32 v[184:185], v[64:65], v[128:129], v[184:185]
	global_store_dwordx4 v[226:227], v[184:187], off offset:576
	v_add_co_u32_e32 v224, vcc, 0x140000, v220
	s_nop 1
	v_addc_co_u32_e32 v225, vcc, 0, v221, vcc
	global_load_dwordx4 v[172:175], v[224:225], off nt
	global_load_dwordx4 v[176:179], v[224:225], off offset:64 nt
	global_load_dwordx4 v[180:183], v[224:225], off offset:512 nt
	global_load_dwordx4 v[184:187], v[224:225], off offset:576 nt
	s_waitcnt vmcnt(16)
	v_add_co_u32_e32 v226, vcc, 0x100000, v222
	s_nop 1
	v_addc_co_u32_e32 v227, vcc, 0, v223, vcc
	v_pk_fma_f32 v[190:191], v[62:63], v[142:143], v[190:191]
	v_pk_fma_f32 v[188:189], v[60:61], v[140:141], v[188:189]
	global_store_dwordx4 v[226:227], v[188:191], off
	v_pk_fma_f32 v[194:195], v[58:59], v[138:139], v[194:195]
	v_pk_fma_f32 v[192:193], v[56:57], v[136:137], v[192:193]
	global_store_dwordx4 v[226:227], v[192:195], off offset:64
	v_pk_fma_f32 v[198:199], v[46:47], v[134:135], v[198:199]
	v_pk_fma_f32 v[196:197], v[44:45], v[132:133], v[196:197]
	global_store_dwordx4 v[226:227], v[196:199], off offset:512
	v_pk_fma_f32 v[202:203], v[42:43], v[130:131], v[202:203]
	v_pk_fma_f32 v[200:201], v[40:41], v[128:129], v[200:201]
	global_store_dwordx4 v[226:227], v[200:203], off offset:576
	v_add_co_u32_e32 v224, vcc, 0x160000, v220
	s_nop 1
	v_addc_co_u32_e32 v225, vcc, 0, v221, vcc
	global_load_dwordx4 v[188:191], v[224:225], off nt
	global_load_dwordx4 v[192:195], v[224:225], off offset:64 nt
	global_load_dwordx4 v[196:199], v[224:225], off offset:512 nt
	global_load_dwordx4 v[200:203], v[224:225], off offset:576 nt
	s_waitcnt vmcnt(16)
	v_add_co_u32_e32 v226, vcc, 0x120000, v222
	s_nop 1
	v_addc_co_u32_e32 v227, vcc, 0, v223, vcc
	v_pk_fma_f32 v[206:207], v[54:55], v[142:143], v[206:207]
	v_pk_fma_f32 v[204:205], v[52:53], v[140:141], v[204:205]
	global_store_dwordx4 v[226:227], v[204:207], off
	v_pk_fma_f32 v[210:211], v[50:51], v[138:139], v[210:211]
	v_pk_fma_f32 v[208:209], v[48:49], v[136:137], v[208:209]
	global_store_dwordx4 v[226:227], v[208:211], off offset:64
	v_pk_fma_f32 v[214:215], v[38:39], v[134:135], v[214:215]
	v_pk_fma_f32 v[212:213], v[36:37], v[132:133], v[212:213]
	global_store_dwordx4 v[226:227], v[212:215], off offset:512
	v_pk_fma_f32 v[218:219], v[34:35], v[130:131], v[218:219]
	v_pk_fma_f32 v[216:217], v[32:33], v[128:129], v[216:217]
	global_store_dwordx4 v[226:227], v[216:219], off offset:576
	s_waitcnt vmcnt(12)
	v_add_co_u32_e32 v226, vcc, 0x140000, v222
	s_nop 1
	v_addc_co_u32_e32 v227, vcc, 0, v223, vcc
	v_pk_fma_f32 v[174:175], v[30:31], v[142:143], v[174:175]
	v_pk_fma_f32 v[172:173], v[28:29], v[140:141], v[172:173]
	global_store_dwordx4 v[226:227], v[172:175], off
	v_pk_fma_f32 v[178:179], v[26:27], v[138:139], v[178:179]
	v_pk_fma_f32 v[176:177], v[24:25], v[136:137], v[176:177]
	global_store_dwordx4 v[226:227], v[176:179], off offset:64
	v_pk_fma_f32 v[182:183], v[14:15], v[134:135], v[182:183]
	v_pk_fma_f32 v[180:181], v[12:13], v[132:133], v[180:181]
	global_store_dwordx4 v[226:227], v[180:183], off offset:512
	v_pk_fma_f32 v[186:187], v[10:11], v[130:131], v[186:187]
	v_pk_fma_f32 v[184:185], v[8:9], v[128:129], v[184:185]
	global_store_dwordx4 v[226:227], v[184:187], off offset:576
	s_waitcnt vmcnt(8)
	v_add_co_u32_e32 v226, vcc, 0x160000, v222
	s_nop 1
	v_addc_co_u32_e32 v227, vcc, 0, v223, vcc
	v_pk_fma_f32 v[190:191], v[22:23], v[142:143], v[190:191]
	v_pk_fma_f32 v[188:189], v[20:21], v[140:141], v[188:189]
	global_store_dwordx4 v[226:227], v[188:191], off
	v_pk_fma_f32 v[194:195], v[18:19], v[138:139], v[194:195]
	v_pk_fma_f32 v[192:193], v[16:17], v[136:137], v[192:193]
	global_store_dwordx4 v[226:227], v[192:195], off offset:64
	v_pk_fma_f32 v[198:199], v[6:7], v[134:135], v[198:199]
	v_pk_fma_f32 v[196:197], v[4:5], v[132:133], v[196:197]
	global_store_dwordx4 v[226:227], v[196:199], off offset:512
	v_pk_fma_f32 v[202:203], v[2:3], v[130:131], v[202:203]
	v_pk_fma_f32 v[200:201], v[0:1], v[128:129], v[200:201]
	global_store_dwordx4 v[226:227], v[200:203], off offset:576
	s_cbranch_execnz .LBB0_885

;     __device__ __forceinline__ void operator()(const f32x4 (&acc)[2][2][4][2], const Unit& u, int wr, int wc, int fr, int fq) const {
;         const int row0 = u.pm * BM + wr * 64 + fr, col0 = u.pn * BM + wc * 32 + 4 * fq, tid = threadIdx.x;
;         if (u.pm >= 32) { store_partials(acc, u, row0, col0, gate, part); return; }
;         const float* gp = gate + (size_t)128 * NMOD;
;         int roff = row0 * D + col0; asm volatile("" : "+v"(roff));
; #pragma unroll
;         for (int ai = 0; ai < 2; ++ai)
; #pragma unroll
;             for (int m = 0; m < 4; ++m) { const int ro = roff + (ai * HALF + m * 16) * D; float ps = 0.f;
; #pragma unroll
;                 for (int bj = 0; bj < 2; ++bj)
; #pragma unroll
;                     for (int n = 0; n < 2; ++n) { const int o = bj * HALF + n * 16; const f32x4 rv = *(const f32x4*)(res0 + (ro + o)), gv = *(const f32x4*)(gp + (col0 + o));
;                         const f32x4 v = rv + gv * acc[ai][bj][m][n]; ps += v[0] * v[0] + v[1] * v[1] + v[2] * v[2] + v[3] * v[3]; }
;                 ps += __shfl_xor(ps, 16); ps += __shfl_xor(ps, 32);
;                 if (fq == 0) red[(ai * HALF + wr * 64 + m * 16 + fr) * 4 + wc] = ps; }
.LBB0_1144:
	v_lshl_add_u32 v190, s26, 8, v161
	v_lshl_or_b32 v174, s27, 8, v182
	s_cmp_lt_i32 s26, 32
	s_mov_b64 s[34:35], -1
	s_cbranch_scc0 .LBB0_1182
	v_lshl_add_u32 v172, v190, 11, v174
	v_mov_b32_e32 v128, v172
	v_ashrrev_i32_e32 v175, 31, v174
	v_lshl_add_u64 v[144:145], v[174:175], 2, s[14:15]
	v_ashrrev_i32_e32 v129, 31, v128
	v_lshl_add_u64 v[146:147], v[128:129], 2, s[8:9]
	global_load_dwordx4 v[128:131], v[144:145], off
	global_load_dwordx4 v[132:135], v[144:145], off offset:64
	global_load_dwordx4 v[136:139], v[144:145], off offset:512
	global_load_dwordx4 v[140:143], v[144:145], off offset:576
	global_load_dwordx4 v[192:195], v[146:147], off nt
	global_load_dwordx4 v[196:199], v[146:147], off offset:64 nt
	global_load_dwordx4 v[200:203], v[146:147], off offset:512 nt
	global_load_dwordx4 v[204:207], v[146:147], off offset:576 nt
	v_add_co_u32_e32 v176, vcc, 0x20000, v146
	s_nop 1
	v_addc_co_u32_e32 v177, vcc, 0, v147, vcc
	global_load_dwordx4 v[208:211], v[176:177], off nt
	global_load_dwordx4 v[212:215], v[176:177], off offset:64 nt
	global_load_dwordx4 v[216:219], v[176:177], off offset:512 nt
	global_load_dwordx4 v[220:223], v[176:177], off offset:576 nt
	v_add_co_u32_e32 v176, vcc, 0x40000, v146
	s_nop 1
	v_addc_co_u32_e32 v177, vcc, 0, v147, vcc
	global_load_dwordx4 v[224:227], v[176:177], off nt
	global_load_dwordx4 v[228:231], v[176:177], off offset:64 nt
	global_load_dwordx4 v[232:235], v[176:177], off offset:512 nt
	global_load_dwordx4 v[152:155], v[176:177], off offset:576 nt
	v_xor_b32_e32 v148, 16, v188
	v_xor_b32_e32 v149, 32, v188
	v_lshlrev_b32_e32 v148, 2, v148
	v_lshlrev_b32_e32 v149, 2, v149
	s_waitcnt vmcnt(8)
	v_pk_fma_f32 v[124:125], v[124:125], v[128:129], v[192:193]
	v_pk_fma_f32 v[126:127], v[126:127], v[130:131], v[194:195]
	v_pk_fma_f32 v[120:121], v[120:121], v[132:133], v[196:197]
	v_pk_fma_f32 v[122:123], v[122:123], v[134:135], v[198:199]
	v_pk_fma_f32 v[108:109], v[108:109], v[136:137], v[200:201]
	v_pk_fma_f32 v[110:111], v[110:111], v[138:139], v[202:203]
	v_pk_fma_f32 v[104:105], v[104:105], v[140:141], v[204:205]
	v_pk_fma_f32 v[106:107], v[106:107], v[142:143], v[206:207]
	v_mul_f32_e32 v150, v125, v125
	v_mul_f32_e32 v151, v121, v121
	v_mul_f32_e32 v173, v109, v109
	v_fmac_f32_e32 v150, v124, v124
	v_fmac_f32_e32 v151, v120, v120
	v_mul_f32_e32 v236, v105, v105
	v_fmac_f32_e32 v173, v108, v108
	v_fmac_f32_e32 v150, v126, v126
	v_fmac_f32_e32 v151, v122, v122
	v_fmac_f32_e32 v236, v104, v104
	v_fmac_f32_e32 v173, v110, v110
	v_fmac_f32_e32 v150, v127, v127
	v_fmac_f32_e32 v151, v123, v123
	v_fmac_f32_e32 v236, v106, v106
	v_fmac_f32_e32 v173, v111, v111
	v_add_f32_e32 v150, v150, v151
	v_add_f32_e32 v150, v150, v173
	v_fmac_f32_e32 v236, v107, v107
	v_add_f32_e32 v150, v150, v236
	ds_bpermute_b32 v151, v148, v150
	s_waitcnt lgkmcnt(0)
	v_add_f32_e32 v150, v150, v151
	ds_bpermute_b32 v151, v149, v150
	s_waitcnt lgkmcnt(0)
	v_add_f32_e32 v150, v150, v151
	s_and_saveexec_b64 s[30:31], s[0:1]
	ds_write_b32 v189, v150
	s_or_b64 exec, exec, s[30:31]
	v_add_co_u32_e32 v176, vcc, 0x60000, v146
	s_nop 1
	v_addc_co_u32_e32 v177, vcc, 0, v147, vcc
	global_load_dwordx4 v[192:195], v[176:177], off nt
	global_load_dwordx4 v[196:199], v[176:177], off offset:64 nt
	global_load_dwordx4 v[200:203], v[176:177], off offset:512 nt
	global_load_dwordx4 v[204:207], v[176:177], off offset:576 nt
	s_waitcnt vmcnt(8)
	v_pk_fma_f32 v[116:117], v[116:117], v[128:129], v[208:209]
	v_pk_fma_f32 v[118:119], v[118:119], v[130:131], v[210:211]
	v_pk_fma_f32 v[112:113], v[112:113], v[132:133], v[212:213]
	v_pk_fma_f32 v[114:115], v[114:115], v[134:135], v[214:215]
	v_pk_fma_f32 v[100:101], v[100:101], v[136:137], v[216:217]
	v_pk_fma_f32 v[102:103], v[102:103], v[138:139], v[218:219]
	v_pk_fma_f32 v[96:97], v[96:97], v[140:141], v[220:221]
	v_pk_fma_f32 v[98:99], v[98:99], v[142:143], v[222:223]
	v_mul_f32_e32 v150, v117, v117
	v_mul_f32_e32 v151, v113, v113
	v_mul_f32_e32 v173, v101, v101
	v_fmac_f32_e32 v150, v116, v116
	v_fmac_f32_e32 v151, v112, v112
	v_mul_f32_e32 v236, v97, v97
	v_fmac_f32_e32 v173, v100, v100
	v_fmac_f32_e32 v150, v118, v118
	v_fmac_f32_e32 v151, v114, v114
	v_fmac_f32_e32 v236, v96, v96
	v_fmac_f32_e32 v173, v102, v102
	v_fmac_f32_e32 v150, v119, v119
	v_fmac_f32_e32 v151, v115, v115
	v_fmac_f32_e32 v236, v98, v98
	v_fmac_f32_e32 v173, v103, v103
	v_add_f32_e32 v150, v150, v151
	v_add_f32_e32 v150, v150, v173
	v_fmac_f32_e32 v236, v99, v99
	v_add_f32_e32 v150, v150, v236
	ds_bpermute_b32 v151, v148, v150
	s_waitcnt lgkmcnt(0)
	v_add_f32_e32 v150, v150, v151
	ds_bpermute_b32 v151, v149, v150
	s_waitcnt lgkmcnt(0)
	v_add_f32_e32 v150, v150, v151
	s_and_saveexec_b64 s[30:31], s[0:1]
	ds_write_b32 v189, v150 offset:256
	s_or_b64 exec, exec, s[30:31]
	v_add_co_u32_e32 v176, vcc, 0x100000, v146
	s_nop 1
	v_addc_co_u32_e32 v177, vcc, 0, v147, vcc
	global_load_dwordx4 v[208:211], v[176:177], off nt
	global_load_dwordx4 v[212:215], v[176:177], off offset:64 nt
	global_load_dwordx4 v[216:219], v[176:177], off offset:512 nt
	global_load_dwordx4 v[220:223], v[176:177], off offset:576 nt
	s_waitcnt vmcnt(8)
;     __device__ __forceinline__ void operator()(const f32x4 (&acc)[2][2][4][2], const Unit& u, int wr, int wc, int fr, int fq) const {
;     ...
; #pragma unroll
;         for (int ai = 0; ai < 2; ++ai)
; #pragma unroll
;             for (int m = 0; m < 4; ++m) { const int ro = roff + (ai * HALF + m * 16) * D; float ps = 0.f;
; #pragma unroll
;                 for (int bj = 0; bj < 2; ++bj)
; #pragma unroll
;                     for (int n = 0; n < 2; ++n) { const int o = bj * HALF + n * 16; const f32x4 rv = *(const f32x4*)(res0 + (ro + o)), gv = *(const f32x4*)(gp + (col0 + o));
;                         const f32x4 v = rv + gv * acc[ai][bj][m][n]; ps += v[0] * v[0] + v[1] * v[1] + v[2] * v[2] + v[3] * v[3]; }
;                 ps += __shfl_xor(ps, 16); ps += __shfl_xor(ps, 32);
;                 if (fq == 0) red[(ai * HALF + wr * 64 + m * 16 + fr) * 4 + wc] = ps; }
	v_pk_fma_f32 v[92:93], v[92:93], v[128:129], v[224:225]
	v_pk_fma_f32 v[94:95], v[94:95], v[130:131], v[226:227]
	v_pk_fma_f32 v[88:89], v[88:89], v[132:133], v[228:229]
	v_pk_fma_f32 v[90:91], v[90:91], v[134:135], v[230:231]
	v_pk_fma_f32 v[76:77], v[76:77], v[136:137], v[232:233]
	v_pk_fma_f32 v[78:79], v[78:79], v[138:139], v[234:235]
	v_pk_fma_f32 v[72:73], v[72:73], v[140:141], v[152:153]
	v_pk_fma_f32 v[74:75], v[74:75], v[142:143], v[154:155]
	v_mul_f32_e32 v150, v93, v93
	v_mul_f32_e32 v151, v89, v89
	v_mul_f32_e32 v173, v77, v77
	v_fmac_f32_e32 v150, v92, v92
	v_fmac_f32_e32 v151, v88, v88
	v_mul_f32_e32 v236, v73, v73
	v_fmac_f32_e32 v173, v76, v76
	v_fmac_f32_e32 v150, v94, v94
	v_fmac_f32_e32 v151, v90, v90
	v_fmac_f32_e32 v236, v72, v72
	v_fmac_f32_e32 v173, v78, v78
	v_fmac_f32_e32 v150, v95, v95
	v_fmac_f32_e32 v151, v91, v91
	v_fmac_f32_e32 v236, v74, v74
	v_fmac_f32_e32 v173, v79, v79
	v_add_f32_e32 v150, v150, v151
	v_add_f32_e32 v150, v150, v173
	v_fmac_f32_e32 v236, v75, v75
	v_add_f32_e32 v150, v150, v236
	ds_bpermute_b32 v151, v148, v150
	s_waitcnt lgkmcnt(0)
	v_add_f32_e32 v150, v150, v151
	ds_bpermute_b32 v151, v149, v150
	s_waitcnt lgkmcnt(0)
	v_add_f32_e32 v150, v150, v151
	s_and_saveexec_b64 s[30:31], s[0:1]
	ds_write_b32 v189, v150 offset:512
	s_or_b64 exec, exec, s[30:31]
	v_add_co_u32_e32 v176, vcc, 0x120000, v146
	s_nop 1
	v_addc_co_u32_e32 v177, vcc, 0, v147, vcc
	global_load_dwordx4 v[224:227], v[176:177], off nt
	global_load_dwordx4 v[228:231], v[176:177], off offset:64 nt
	global_load_dwordx4 v[232:235], v[176:177], off offset:512 nt
	global_load_dwordx4 v[152:155], v[176:177], off offset:576 nt
	s_waitcnt vmcnt(8)
	v_pk_fma_f32 v[84:85], v[84:85], v[128:129], v[192:193]
	v_pk_fma_f32 v[86:87], v[86:87], v[130:131], v[194:195]
	v_pk_fma_f32 v[80:81], v[80:81], v[132:133], v[196:197]
	v_pk_fma_f32 v[82:83], v[82:83], v[134:135], v[198:199]
	v_pk_fma_f32 v[68:69], v[68:69], v[136:137], v[200:201]
	v_pk_fma_f32 v[70:71], v[70:71], v[138:139], v[202:203]
	v_pk_fma_f32 v[64:65], v[64:65], v[140:141], v[204:205]
	v_pk_fma_f32 v[66:67], v[66:67], v[142:143], v[206:207]
	v_mul_f32_e32 v150, v85, v85
	v_mul_f32_e32 v151, v81, v81
	v_mul_f32_e32 v173, v69, v69
	v_fmac_f32_e32 v150, v84, v84
	v_fmac_f32_e32 v151, v80, v80
	v_mul_f32_e32 v236, v65, v65
	v_fmac_f32_e32 v173, v68, v68
	v_fmac_f32_e32 v150, v86, v86
	v_fmac_f32_e32 v151, v82, v82
	v_fmac_f32_e32 v236, v64, v64
	v_fmac_f32_e32 v173, v70, v70
	v_fmac_f32_e32 v150, v87, v87
	v_fmac_f32_e32 v151, v83, v83
	v_fmac_f32_e32 v236, v66, v66
	v_fmac_f32_e32 v173, v71, v71
	v_add_f32_e32 v150, v150, v151
	v_add_f32_e32 v150, v150, v173
	v_fmac_f32_e32 v236, v67, v67
	v_add_f32_e32 v150, v150, v236
	ds_bpermute_b32 v151, v148, v150
	s_waitcnt lgkmcnt(0)
	v_add_f32_e32 v150, v150, v151
	ds_bpermute_b32 v151, v149, v150
	s_waitcnt lgkmcnt(0)
	v_add_f32_e32 v150, v150, v151
	s_and_saveexec_b64 s[30:31], s[0:1]
	ds_write_b32 v189, v150 offset:768
	s_or_b64 exec, exec, s[30:31]
	v_add_co_u32_e32 v176, vcc, 0x140000, v146
	s_nop 1
	v_addc_co_u32_e32 v177, vcc, 0, v147, vcc
	global_load_dwordx4 v[192:195], v[176:177], off nt
	global_load_dwordx4 v[196:199], v[176:177], off offset:64 nt
	global_load_dwordx4 v[200:203], v[176:177], off offset:512 nt
	global_load_dwordx4 v[204:207], v[176:177], off offset:576 nt
	s_waitcnt vmcnt(8)
	v_pk_fma_f32 v[60:61], v[60:61], v[128:129], v[208:209]
	v_pk_fma_f32 v[62:63], v[62:63], v[130:131], v[210:211]
	v_pk_fma_f32 v[56:57], v[56:57], v[132:133], v[212:213]
	v_pk_fma_f32 v[58:59], v[58:59], v[134:135], v[214:215]
	v_pk_fma_f32 v[44:45], v[44:45], v[136:137], v[216:217]
	v_pk_fma_f32 v[46:47], v[46:47], v[138:139], v[218:219]
	v_pk_fma_f32 v[40:41], v[40:41], v[140:141], v[220:221]
	v_pk_fma_f32 v[42:43], v[42:43], v[142:143], v[222:223]
	v_mul_f32_e32 v150, v61, v61
	v_mul_f32_e32 v151, v57, v57
	v_mul_f32_e32 v173, v45, v45
	v_fmac_f32_e32 v150, v60, v60
	v_fmac_f32_e32 v151, v56, v56
	v_mul_f32_e32 v236, v41, v41
	v_fmac_f32_e32 v173, v44, v44
	v_fmac_f32_e32 v150, v62, v62
	v_fmac_f32_e32 v151, v58, v58
	v_fmac_f32_e32 v236, v40, v40
	v_fmac_f32_e32 v173, v46, v46
	v_fmac_f32_e32 v150, v63, v63
	v_fmac_f32_e32 v151, v59, v59
	v_fmac_f32_e32 v236, v42, v42
	v_fmac_f32_e32 v173, v47, v47
	v_add_f32_e32 v150, v150, v151
	v_add_f32_e32 v150, v150, v173
	v_fmac_f32_e32 v236, v43, v43
	v_add_f32_e32 v150, v150, v236
	ds_bpermute_b32 v151, v148, v150
	s_waitcnt lgkmcnt(0)
	v_add_f32_e32 v150, v150, v151
	ds_bpermute_b32 v151, v149, v150
	s_waitcnt lgkmcnt(0)
;     __device__ __forceinline__ void operator()(const f32x4 (&acc)[2][2][4][2], const Unit& u, int wr, int wc, int fr, int fq) const {
;     ...
; #pragma unroll
;         for (int ai = 0; ai < 2; ++ai)
; #pragma unroll
;             for (int m = 0; m < 4; ++m) { const int ro = roff + (ai * HALF + m * 16) * D; float ps = 0.f;
; #pragma unroll
;                 for (int bj = 0; bj < 2; ++bj)
; #pragma unroll
;                     for (int n = 0; n < 2; ++n) { const int o = bj * HALF + n * 16; const f32x4 rv = *(const f32x4*)(res0 + (ro + o)), gv = *(const f32x4*)(gp + (col0 + o));
;                         const f32x4 v = rv + gv * acc[ai][bj][m][n]; ps += v[0] * v[0] + v[1] * v[1] + v[2] * v[2] + v[3] * v[3]; }
;                 ps += __shfl_xor(ps, 16); ps += __shfl_xor(ps, 32);
;                 if (fq == 0) red[(ai * HALF + wr * 64 + m * 16 + fr) * 4 + wc] = ps; }
	v_add_f32_e32 v150, v150, v151
	s_and_saveexec_b64 s[30:31], s[0:1]
	ds_write_b32 v189, v150 offset:2048
	s_or_b64 exec, exec, s[30:31]
	v_add_co_u32_e32 v176, vcc, 0x160000, v146
	s_nop 1
	v_addc_co_u32_e32 v177, vcc, 0, v147, vcc
	global_load_dwordx4 v[208:211], v[176:177], off nt
	global_load_dwordx4 v[212:215], v[176:177], off offset:64 nt
	global_load_dwordx4 v[216:219], v[176:177], off offset:512 nt
	global_load_dwordx4 v[220:223], v[176:177], off offset:576 nt
	s_waitcnt vmcnt(8)
	v_pk_fma_f32 v[52:53], v[52:53], v[128:129], v[224:225]
	v_pk_fma_f32 v[54:55], v[54:55], v[130:131], v[226:227]
	v_pk_fma_f32 v[48:49], v[48:49], v[132:133], v[228:229]
	v_pk_fma_f32 v[50:51], v[50:51], v[134:135], v[230:231]
	v_pk_fma_f32 v[36:37], v[36:37], v[136:137], v[232:233]
	v_pk_fma_f32 v[38:39], v[38:39], v[138:139], v[234:235]
	v_pk_fma_f32 v[32:33], v[32:33], v[140:141], v[152:153]
	v_pk_fma_f32 v[34:35], v[34:35], v[142:143], v[154:155]
	v_mul_f32_e32 v150, v53, v53
	v_mul_f32_e32 v151, v49, v49
	v_mul_f32_e32 v173, v37, v37
	v_fmac_f32_e32 v150, v52, v52
	v_fmac_f32_e32 v151, v48, v48
	v_mul_f32_e32 v236, v33, v33
	v_fmac_f32_e32 v173, v36, v36
	v_fmac_f32_e32 v150, v54, v54
	v_fmac_f32_e32 v151, v50, v50
	v_fmac_f32_e32 v236, v32, v32
	v_fmac_f32_e32 v173, v38, v38
	v_fmac_f32_e32 v150, v55, v55
	v_fmac_f32_e32 v151, v51, v51
	v_fmac_f32_e32 v236, v34, v34
	v_fmac_f32_e32 v173, v39, v39
	v_add_f32_e32 v150, v150, v151
	v_add_f32_e32 v150, v150, v173
	v_fmac_f32_e32 v236, v35, v35
	v_add_f32_e32 v150, v150, v236
	ds_bpermute_b32 v151, v148, v150
	s_waitcnt lgkmcnt(0)
	v_add_f32_e32 v150, v150, v151
	ds_bpermute_b32 v151, v149, v150
	s_waitcnt lgkmcnt(0)
	v_add_f32_e32 v150, v150, v151
	s_and_saveexec_b64 s[30:31], s[0:1]
	ds_write_b32 v189, v150 offset:2304
	s_or_b64 exec, exec, s[30:31]
	s_waitcnt vmcnt(4)
	v_pk_fma_f32 v[28:29], v[28:29], v[128:129], v[192:193]
	v_pk_fma_f32 v[30:31], v[30:31], v[130:131], v[194:195]
	v_pk_fma_f32 v[24:25], v[24:25], v[132:133], v[196:197]
	v_pk_fma_f32 v[26:27], v[26:27], v[134:135], v[198:199]
	v_pk_fma_f32 v[12:13], v[12:13], v[136:137], v[200:201]
	v_pk_fma_f32 v[14:15], v[14:15], v[138:139], v[202:203]
	v_pk_fma_f32 v[8:9], v[8:9], v[140:141], v[204:205]
	v_pk_fma_f32 v[10:11], v[10:11], v[142:143], v[206:207]
	v_mul_f32_e32 v150, v29, v29
	v_mul_f32_e32 v151, v25, v25
	v_mul_f32_e32 v173, v13, v13
	v_fmac_f32_e32 v150, v28, v28
	v_fmac_f32_e32 v151, v24, v24
	v_mul_f32_e32 v236, v9, v9
	v_fmac_f32_e32 v173, v12, v12
	v_fmac_f32_e32 v150, v30, v30
	v_fmac_f32_e32 v151, v26, v26
	v_fmac_f32_e32 v236, v8, v8
	v_fmac_f32_e32 v173, v14, v14
	v_fmac_f32_e32 v150, v31, v31
	v_fmac_f32_e32 v151, v27, v27
	v_fmac_f32_e32 v236, v10, v10
	v_fmac_f32_e32 v173, v15, v15
	v_add_f32_e32 v150, v150, v151
	v_add_f32_e32 v150, v150, v173
	v_fmac_f32_e32 v236, v11, v11
	v_add_f32_e32 v150, v150, v236
	ds_bpermute_b32 v151, v148, v150
	s_waitcnt lgkmcnt(0)
	v_add_f32_e32 v150, v150, v151
	ds_bpermute_b32 v151, v149, v150
	s_waitcnt lgkmcnt(0)
	v_add_f32_e32 v150, v150, v151
	s_and_saveexec_b64 s[30:31], s[0:1]
	ds_write_b32 v189, v150 offset:2560
	s_or_b64 exec, exec, s[30:31]
	s_waitcnt vmcnt(0)
	v_pk_fma_f32 v[20:21], v[20:21], v[128:129], v[208:209]
	v_pk_fma_f32 v[22:23], v[22:23], v[130:131], v[210:211]
	v_pk_fma_f32 v[16:17], v[16:17], v[132:133], v[212:213]
	v_pk_fma_f32 v[18:19], v[18:19], v[134:135], v[214:215]
	v_pk_fma_f32 v[4:5], v[4:5], v[136:137], v[216:217]
	v_pk_fma_f32 v[6:7], v[6:7], v[138:139], v[218:219]
	v_pk_fma_f32 v[0:1], v[0:1], v[140:141], v[220:221]
	v_pk_fma_f32 v[2:3], v[2:3], v[142:143], v[222:223]
	v_mul_f32_e32 v150, v21, v21
	v_mul_f32_e32 v151, v17, v17
	v_mul_f32_e32 v173, v5, v5
	v_fmac_f32_e32 v150, v20, v20
	v_fmac_f32_e32 v151, v16, v16
	v_mul_f32_e32 v236, v1, v1
	v_fmac_f32_e32 v173, v4, v4
	v_fmac_f32_e32 v150, v22, v22
	v_fmac_f32_e32 v151, v18, v18
	v_fmac_f32_e32 v236, v0, v0
	v_fmac_f32_e32 v173, v6, v6
	v_fmac_f32_e32 v150, v23, v23
	v_fmac_f32_e32 v151, v19, v19
	v_fmac_f32_e32 v236, v2, v2
	v_fmac_f32_e32 v173, v7, v7
	v_add_f32_e32 v150, v150, v151
	v_add_f32_e32 v150, v150, v173
	v_fmac_f32_e32 v236, v3, v3
	v_add_f32_e32 v150, v150, v236
	ds_bpermute_b32 v151, v148, v150
	s_waitcnt lgkmcnt(0)
	v_add_f32_e32 v150, v150, v151
	ds_bpermute_b32 v151, v149, v150
	s_waitcnt lgkmcnt(0)
	v_add_f32_e32 v150, v150, v151
	s_and_saveexec_b64 s[30:31], s[0:1]
	ds_write_b32 v189, v150 offset:2816
	s_or_b64 exec, exec, s[30:31]

;     __device__ __forceinline__ void operator()(const f32x4 (&acc)[2][2][4][2], const Unit& u, int wr, int wc, int fr, int fq) const {
;     ...
;         int woff = row0 * D + col0; asm volatile("" : "+v"(woff));
;         f32x4 gw[2][2], ww[2][2];
; #pragma unroll
;         for (int bj = 0; bj < 2; ++bj)
; #pragma unroll
;             for (int n = 0; n < 2; ++n) { gw[bj][n] = *(const f32x4*)(gp + (col0 + bj * HALF + n * 16)); ww[bj][n] = *(const f32x4*)(nw + (col0 + bj * HALF + n * 16)); }
; #pragma unroll
;         for (int am = 0; am < 4; ++am) { f32x4 rv[2][2][2]; float rr[2];
; #pragma unroll
;             for (int m2 = 0; m2 < 2; ++m2) { rr[m2] = red[1024 + (am >> 1) * HALF + wr * 64 + ((am & 1) * 2 + m2) * 16 + fr];
; #pragma unroll
;                 for (int bj = 0; bj < 2; ++bj)
; #pragma unroll
;                     for (int n = 0; n < 2; ++n) rv[m2][bj][n] = *(const f32x4*)(res0 + (woff + ((am >> 1) * HALF + ((am & 1) * 2 + m2) * 16) * D + bj * HALF + n * 16)); }
; #pragma unroll
;             for (int m2 = 0; m2 < 2; ++m2)
; #pragma unroll
;                 for (int bj = 0; bj < 2; ++bj)
; #pragma unroll
;                     for (int n = 0; n < 2; ++n) *(f32x4*)(out + (woff + ((am >> 1) * HALF + ((am & 1) * 2 + m2) * 16) * D + bj * HALF + n * 16)) = (rv[m2][bj][n] + gw[bj][n] * acc[am >> 1][bj][(am & 1) * 2 + m2][n]) * rr[m2] * ww[bj][n]; }
.LBB0_1181:
	s_or_b64 exec, exec, s[30:31]
	s_waitcnt lgkmcnt(0)
	s_barrier
	v_readlane_b32 s70, v245, 9
	v_readlane_b32 s71, v245, 10
	s_nop 3
	v_lshl_add_u64 v[144:145], v[174:175], 2, s[70:71]
	global_load_dwordx4 v[208:211], v[144:145], off
	global_load_dwordx4 v[212:215], v[144:145], off offset:64
	global_load_dwordx4 v[216:219], v[144:145], off offset:512
	global_load_dwordx4 v[220:223], v[144:145], off offset:576
	ds_read2_b32 v[192:193], v180 offset1:16
	ds_read2_b32 v[194:195], v180 offset0:32 offset1:48
	ds_read2_b32 v[196:197], v181 offset1:16
	ds_read2_b32 v[198:199], v181 offset0:32 offset1:48
	v_readlane_b32 s64, v245, 21
	v_readlane_b32 s65, v245, 22
	v_readlane_b32 s66, v245, 23
	v_readlane_b32 s67, v245, 24
	v_readlane_b32 s68, v245, 25
	v_readlane_b32 s69, v245, 26
	v_readlane_b32 s70, v245, 27
	v_readlane_b32 s71, v245, 28
	v_readlane_b32 s72, v245, 29
	v_readlane_b32 s73, v245, 30
	v_readlane_b32 s74, v245, 31
	v_readlane_b32 s75, v245, 32
	v_readlane_b32 s76, v245, 33
	v_readlane_b32 s77, v245, 34
	v_readlane_b32 s78, v245, 35
	v_readlane_b32 s79, v245, 36
	s_nop 3
	s_mov_b64 s[26:27], s[78:79]
	s_mov_b64 s[34:35], 0
	s_mov_b64 s[30:31], s[78:79]
	v_ashrrev_i32_e32 v173, 31, v172
	v_lshlrev_b64 v[224:225], 2, v[172:173]
	v_lshl_add_u64 v[224:225], s[26:27], 0, v[224:225]
	s_waitcnt vmcnt(0) lgkmcnt(0)
	v_pk_mul_f32 v[124:125], v[192:193], v[124:125] op_sel_hi:[0,1]
	v_pk_mul_f32 v[126:127], v[192:193], v[126:127] op_sel_hi:[0,1]
	v_pk_mul_f32 v[124:125], v[208:209], v[124:125]
	v_pk_mul_f32 v[126:127], v[210:211], v[126:127]
	global_store_dwordx4 v[224:225], v[124:127], off nt
	v_pk_mul_f32 v[120:121], v[192:193], v[120:121] op_sel_hi:[0,1]
	v_pk_mul_f32 v[122:123], v[192:193], v[122:123] op_sel_hi:[0,1]
	v_pk_mul_f32 v[120:121], v[212:213], v[120:121]
	v_pk_mul_f32 v[122:123], v[214:215], v[122:123]
	global_store_dwordx4 v[224:225], v[120:123], off offset:64 nt
	v_pk_mul_f32 v[108:109], v[192:193], v[108:109] op_sel_hi:[0,1]
	v_pk_mul_f32 v[110:111], v[192:193], v[110:111] op_sel_hi:[0,1]
	v_pk_mul_f32 v[108:109], v[216:217], v[108:109]
	v_pk_mul_f32 v[110:111], v[218:219], v[110:111]
	global_store_dwordx4 v[224:225], v[108:111], off offset:512 nt
	v_pk_mul_f32 v[104:105], v[192:193], v[104:105] op_sel_hi:[0,1]
	v_pk_mul_f32 v[106:107], v[192:193], v[106:107] op_sel_hi:[0,1]
	v_pk_mul_f32 v[104:105], v[220:221], v[104:105]
	v_pk_mul_f32 v[106:107], v[222:223], v[106:107]
	global_store_dwordx4 v[224:225], v[104:107], off offset:576 nt
	v_add_co_u32_e32 v226, vcc, 0x20000, v224
	s_nop 1
	v_addc_co_u32_e32 v227, vcc, 0, v225, vcc
	v_pk_mul_f32 v[116:117], v[192:193], v[116:117] op_sel:[1,0]
	v_pk_mul_f32 v[118:119], v[192:193], v[118:119] op_sel:[1,0]
	v_pk_mul_f32 v[116:117], v[208:209], v[116:117]
	v_pk_mul_f32 v[118:119], v[210:211], v[118:119]
	global_store_dwordx4 v[226:227], v[116:119], off nt
	v_pk_mul_f32 v[112:113], v[192:193], v[112:113] op_sel:[1,0]
	v_pk_mul_f32 v[114:115], v[192:193], v[114:115] op_sel:[1,0]
	v_pk_mul_f32 v[112:113], v[212:213], v[112:113]
	v_pk_mul_f32 v[114:115], v[214:215], v[114:115]
	global_store_dwordx4 v[226:227], v[112:115], off offset:64 nt
	v_pk_mul_f32 v[100:101], v[192:193], v[100:101] op_sel:[1,0]
	v_pk_mul_f32 v[102:103], v[192:193], v[102:103] op_sel:[1,0]
	v_pk_mul_f32 v[100:101], v[216:217], v[100:101]
	v_pk_mul_f32 v[102:103], v[218:219], v[102:103]
	global_store_dwordx4 v[226:227], v[100:103], off offset:512 nt
	v_pk_mul_f32 v[96:97], v[192:193], v[96:97] op_sel:[1,0]
	v_pk_mul_f32 v[98:99], v[192:193], v[98:99] op_sel:[1,0]
	v_pk_mul_f32 v[96:97], v[220:221], v[96:97]
	v_pk_mul_f32 v[98:99], v[222:223], v[98:99]
	global_store_dwordx4 v[226:227], v[96:99], off offset:576 nt
	v_add_co_u32_e32 v226, vcc, 0x40000, v224
	s_nop 1
	v_addc_co_u32_e32 v227, vcc, 0, v225, vcc
	v_pk_mul_f32 v[92:93], v[194:195], v[92:93] op_sel_hi:[0,1]
	v_pk_mul_f32 v[94:95], v[194:195], v[94:95] op_sel_hi:[0,1]
	v_pk_mul_f32 v[92:93], v[208:209], v[92:93]
	v_pk_mul_f32 v[94:95], v[210:211], v[94:95]
	global_store_dwordx4 v[226:227], v[92:95], off nt
	v_pk_mul_f32 v[88:89], v[194:195], v[88:89] op_sel_hi:[0,1]
	v_pk_mul_f32 v[90:91], v[194:195], v[90:91] op_sel_hi:[0,1]
	v_pk_mul_f32 v[88:89], v[212:213], v[88:89]
	v_pk_mul_f32 v[90:91], v[214:215], v[90:91]
	global_store_dwordx4 v[226:227], v[88:91], off offset:64 nt
	v_pk_mul_f32 v[76:77], v[194:195], v[76:77] op_sel_hi:[0,1]
	v_pk_mul_f32 v[78:79], v[194:195], v[78:79] op_sel_hi:[0,1]
	v_pk_mul_f32 v[76:77], v[216:217], v[76:77]
	v_pk_mul_f32 v[78:79], v[218:219], v[78:79]
	global_store_dwordx4 v[226:227], v[76:79], off offset:512 nt
	v_pk_mul_f32 v[72:73], v[194:195], v[72:73] op_sel_hi:[0,1]
	v_pk_mul_f32 v[74:75], v[194:195], v[74:75] op_sel_hi:[0,1]
	v_pk_mul_f32 v[72:73], v[220:221], v[72:73]
	v_pk_mul_f32 v[74:75], v[222:223], v[74:75]
	global_store_dwordx4 v[226:227], v[72:75], off offset:576 nt
	v_add_co_u32_e32 v226, vcc, 0x60000, v224
	s_nop 1
	v_addc_co_u32_e32 v227, vcc, 0, v225, vcc
	v_pk_mul_f32 v[84:85], v[194:195], v[84:85] op_sel:[1,0]
	v_pk_mul_f32 v[86:87], v[194:195], v[86:87] op_sel:[1,0]
	v_pk_mul_f32 v[84:85], v[208:209], v[84:85]
	v_pk_mul_f32 v[86:87], v[210:211], v[86:87]
	global_store_dwordx4 v[226:227], v[84:87], off nt
	v_pk_mul_f32 v[80:81], v[194:195], v[80:81] op_sel:[1,0]
;     __device__ __forceinline__ void operator()(const f32x4 (&acc)[2][2][4][2], const Unit& u, int wr, int wc, int fr, int fq) const {
;     ...
;         for (int am = 0; am < 4; ++am) { f32x4 rv[2][2][2]; float rr[2];
; #pragma unroll
;             for (int m2 = 0; m2 < 2; ++m2) { rr[m2] = red[1024 + (am >> 1) * HALF + wr * 64 + ((am & 1) * 2 + m2) * 16 + fr];
; #pragma unroll
;                 for (int bj = 0; bj < 2; ++bj)
; #pragma unroll
;                     for (int n = 0; n < 2; ++n) rv[m2][bj][n] = *(const f32x4*)(res0 + (woff + ((am >> 1) * HALF + ((am & 1) * 2 + m2) * 16) * D + bj * HALF + n * 16)); }
; #pragma unroll
;             for (int m2 = 0; m2 < 2; ++m2)
; #pragma unroll
;                 for (int bj = 0; bj < 2; ++bj)
; #pragma unroll
;                     for (int n = 0; n < 2; ++n) *(f32x4*)(out + (woff + ((am >> 1) * HALF + ((am & 1) * 2 + m2) * 16) * D + bj * HALF + n * 16)) = (rv[m2][bj][n] + gw[bj][n] * acc[am >> 1][bj][(am & 1) * 2 + m2][n]) * rr[m2] * ww[bj][n]; }
	v_pk_mul_f32 v[82:83], v[194:195], v[82:83] op_sel:[1,0]
	v_pk_mul_f32 v[80:81], v[212:213], v[80:81]
	v_pk_mul_f32 v[82:83], v[214:215], v[82:83]
	global_store_dwordx4 v[226:227], v[80:83], off offset:64 nt
	v_pk_mul_f32 v[68:69], v[194:195], v[68:69] op_sel:[1,0]
	v_pk_mul_f32 v[70:71], v[194:195], v[70:71] op_sel:[1,0]
	v_pk_mul_f32 v[68:69], v[216:217], v[68:69]
	v_pk_mul_f32 v[70:71], v[218:219], v[70:71]
	global_store_dwordx4 v[226:227], v[68:71], off offset:512 nt
	v_pk_mul_f32 v[64:65], v[194:195], v[64:65] op_sel:[1,0]
	v_pk_mul_f32 v[66:67], v[194:195], v[66:67] op_sel:[1,0]
	v_pk_mul_f32 v[64:65], v[220:221], v[64:65]
	v_pk_mul_f32 v[66:67], v[222:223], v[66:67]
	global_store_dwordx4 v[226:227], v[64:67], off offset:576 nt
	v_add_co_u32_e32 v226, vcc, 0x100000, v224
	s_nop 1
	v_addc_co_u32_e32 v227, vcc, 0, v225, vcc
	v_pk_mul_f32 v[60:61], v[196:197], v[60:61] op_sel_hi:[0,1]
	v_pk_mul_f32 v[62:63], v[196:197], v[62:63] op_sel_hi:[0,1]
	v_pk_mul_f32 v[60:61], v[208:209], v[60:61]
	v_pk_mul_f32 v[62:63], v[210:211], v[62:63]
	global_store_dwordx4 v[226:227], v[60:63], off nt
	v_pk_mul_f32 v[56:57], v[196:197], v[56:57] op_sel_hi:[0,1]
	v_pk_mul_f32 v[58:59], v[196:197], v[58:59] op_sel_hi:[0,1]
	v_pk_mul_f32 v[56:57], v[212:213], v[56:57]
	v_pk_mul_f32 v[58:59], v[214:215], v[58:59]
	global_store_dwordx4 v[226:227], v[56:59], off offset:64 nt
	v_pk_mul_f32 v[44:45], v[196:197], v[44:45] op_sel_hi:[0,1]
	v_pk_mul_f32 v[46:47], v[196:197], v[46:47] op_sel_hi:[0,1]
	v_pk_mul_f32 v[44:45], v[216:217], v[44:45]
	v_pk_mul_f32 v[46:47], v[218:219], v[46:47]
	global_store_dwordx4 v[226:227], v[44:47], off offset:512 nt
	v_pk_mul_f32 v[40:41], v[196:197], v[40:41] op_sel_hi:[0,1]
	v_pk_mul_f32 v[42:43], v[196:197], v[42:43] op_sel_hi:[0,1]
	v_pk_mul_f32 v[40:41], v[220:221], v[40:41]
	v_pk_mul_f32 v[42:43], v[222:223], v[42:43]
	global_store_dwordx4 v[226:227], v[40:43], off offset:576 nt
	v_add_co_u32_e32 v226, vcc, 0x120000, v224
	s_nop 1
	v_addc_co_u32_e32 v227, vcc, 0, v225, vcc
	v_pk_mul_f32 v[52:53], v[196:197], v[52:53] op_sel:[1,0]
	v_pk_mul_f32 v[54:55], v[196:197], v[54:55] op_sel:[1,0]
	v_pk_mul_f32 v[52:53], v[208:209], v[52:53]
	v_pk_mul_f32 v[54:55], v[210:211], v[54:55]
	global_store_dwordx4 v[226:227], v[52:55], off nt
	v_pk_mul_f32 v[48:49], v[196:197], v[48:49] op_sel:[1,0]
	v_pk_mul_f32 v[50:51], v[196:197], v[50:51] op_sel:[1,0]
	v_pk_mul_f32 v[48:49], v[212:213], v[48:49]
	v_pk_mul_f32 v[50:51], v[214:215], v[50:51]
	global_store_dwordx4 v[226:227], v[48:51], off offset:64 nt
	v_pk_mul_f32 v[36:37], v[196:197], v[36:37] op_sel:[1,0]
	v_pk_mul_f32 v[38:39], v[196:197], v[38:39] op_sel:[1,0]
	v_pk_mul_f32 v[36:37], v[216:217], v[36:37]
	v_pk_mul_f32 v[38:39], v[218:219], v[38:39]
	global_store_dwordx4 v[226:227], v[36:39], off offset:512 nt
	v_pk_mul_f32 v[32:33], v[196:197], v[32:33] op_sel:[1,0]
	v_pk_mul_f32 v[34:35], v[196:197], v[34:35] op_sel:[1,0]
	v_pk_mul_f32 v[32:33], v[220:221], v[32:33]
	v_pk_mul_f32 v[34:35], v[222:223], v[34:35]
	global_store_dwordx4 v[226:227], v[32:35], off offset:576 nt
	v_add_co_u32_e32 v226, vcc, 0x140000, v224
	s_nop 1
	v_addc_co_u32_e32 v227, vcc, 0, v225, vcc
	v_pk_mul_f32 v[28:29], v[198:199], v[28:29] op_sel_hi:[0,1]
	v_pk_mul_f32 v[30:31], v[198:199], v[30:31] op_sel_hi:[0,1]
	v_pk_mul_f32 v[28:29], v[208:209], v[28:29]
	v_pk_mul_f32 v[30:31], v[210:211], v[30:31]
	global_store_dwordx4 v[226:227], v[28:31], off nt
	v_pk_mul_f32 v[24:25], v[198:199], v[24:25] op_sel_hi:[0,1]
	v_pk_mul_f32 v[26:27], v[198:199], v[26:27] op_sel_hi:[0,1]
	v_pk_mul_f32 v[24:25], v[212:213], v[24:25]
	v_pk_mul_f32 v[26:27], v[214:215], v[26:27]
	global_store_dwordx4 v[226:227], v[24:27], off offset:64 nt
	v_pk_mul_f32 v[12:13], v[198:199], v[12:13] op_sel_hi:[0,1]
	v_pk_mul_f32 v[14:15], v[198:199], v[14:15] op_sel_hi:[0,1]
	v_pk_mul_f32 v[12:13], v[216:217], v[12:13]
	v_pk_mul_f32 v[14:15], v[218:219], v[14:15]
	global_store_dwordx4 v[226:227], v[12:15], off offset:512 nt
	v_pk_mul_f32 v[8:9], v[198:199], v[8:9] op_sel_hi:[0,1]
	v_pk_mul_f32 v[10:11], v[198:199], v[10:11] op_sel_hi:[0,1]
	v_pk_mul_f32 v[8:9], v[220:221], v[8:9]
	v_pk_mul_f32 v[10:11], v[222:223], v[10:11]
	global_store_dwordx4 v[226:227], v[8:11], off offset:576 nt
	v_add_co_u32_e32 v226, vcc, 0x160000, v224
	s_nop 1
	v_addc_co_u32_e32 v227, vcc, 0, v225, vcc
	v_pk_mul_f32 v[20:21], v[198:199], v[20:21] op_sel:[1,0]
	v_pk_mul_f32 v[22:23], v[198:199], v[22:23] op_sel:[1,0]
	v_pk_mul_f32 v[20:21], v[208:209], v[20:21]
	v_pk_mul_f32 v[22:23], v[210:211], v[22:23]
	global_store_dwordx4 v[226:227], v[20:23], off nt
	v_pk_mul_f32 v[16:17], v[198:199], v[16:17] op_sel:[1,0]
	v_pk_mul_f32 v[18:19], v[198:199], v[18:19] op_sel:[1,0]
	v_pk_mul_f32 v[16:17], v[212:213], v[16:17]
	v_pk_mul_f32 v[18:19], v[214:215], v[18:19]
	global_store_dwordx4 v[226:227], v[16:19], off offset:64 nt
	v_pk_mul_f32 v[4:5], v[198:199], v[4:5] op_sel:[1,0]
	v_pk_mul_f32 v[6:7], v[198:199], v[6:7] op_sel:[1,0]
	v_pk_mul_f32 v[4:5], v[216:217], v[4:5]
	v_pk_mul_f32 v[6:7], v[218:219], v[6:7]
	global_store_dwordx4 v[226:227], v[4:7], off offset:512 nt
	v_pk_mul_f32 v[128:129], v[198:199], v[0:1] op_sel:[1,0]
	v_pk_mul_f32 v[130:131], v[198:199], v[2:3] op_sel:[1,0]
	v_pk_mul_f32 v[128:129], v[220:221], v[128:129]
	v_pk_mul_f32 v[130:131], v[222:223], v[130:131]
